# hg_item(true) step 4: decay reads and all 12 fragment reads issued ahead of the 8 S-update MFMAs with counted lgkmcnt waits
# speedup vs baseline: 1.0145x; 1.0019x over previous
; #define LAS __attribute__((address_space(3)))
; template <bool FULL, bool STORE = true>
; __device__ __forceinline__ void hg_item(const Prm& P, LAS unsigned char* lds, int item, int wave) {
;     ...
;         for (int g4 = 0; g4 < 4; ++g4) { const f32x4 d = *(const LAS f32x4*)(lds + HL_DC + (kb * 32 + 8 * g4 + 4 * lh) * 4);
; #pragma unroll
;             for (int i = 0; i < 2; ++i)
; #pragma unroll
;                 for (int j = 0; j < 4; ++j) S[i][4 * g4 + j] *= d[j]; }
; #pragma unroll
;         for (int ks = 0; ks < 4; ++ks) { const bf16x8 a = *(const LAS bf16x8*)(lds + HL_KDT + (kb * 32 + l31) * 144 + ks * 32 + lh * 16);
; #pragma unroll
;             for (int i = 0; i < 2; ++i) { const bf16x8 bb = *(const LAS bf16x8*)(lds + HL_IVT + ((vb0 + i) * 32 + l31) * 144 + ks * 32 + lh * 16); S[i] = __builtin_amdgcn_mfma_f32_32x32x16_bf16(a, bb, S[i], 0, 0, 0); } }
.LBB0_839:
	s_mov_b32 s33, 0x800000
	s_add_u32 s86, s86, 0x20000
	s_addc_u32 s87, s87, 0
	v_lshlrev_b32_e32 v104, 16, v52
	v_and_b32_e32 v105, 0xffff0000, v52
	v_lshlrev_b32_e32 v52, 16, v53
	v_and_b32_e32 v53, 0xffff0000, v53
	s_add_u32 s84, s84, 0x10000
	s_addc_u32 s85, s85, 0
	s_cmp_lg_u32 s86, 0x200000
	s_waitcnt lgkmcnt(6)
	v_mfma_f32_32x32x16_bf16 v[32:47], v[172:175], v[176:179], v[32:47]
	ds_read_b128 v[172:175], v151 offset:34944
	ds_read_b128 v[176:179], v152 offset:128
	s_waitcnt lgkmcnt(6)
	v_mfma_f32_32x32x16_bf16 v[32:47], v[180:183], v[184:187], v[32:47]
	ds_read_b128 v[180:183], v151 offset:34976
	ds_read_b128 v[184:187], v152 offset:160
	s_waitcnt lgkmcnt(6)
	v_mfma_f32_32x32x16_bf16 v[32:47], v[188:191], v[192:195], v[32:47]
	ds_read_b128 v[188:191], v151 offset:35008
	ds_read_b128 v[192:195], v152 offset:192
	s_waitcnt lgkmcnt(6)
	v_mfma_f32_32x32x16_bf16 v[32:47], v[196:199], v[200:203], v[32:47]
	ds_read_b128 v[196:199], v151 offset:35040
	ds_read_b128 v[200:203], v152 offset:224
	s_waitcnt lgkmcnt(6)
	v_mfma_f32_32x32x16_bf16 v[32:47], v[172:175], v[176:179], v[32:47]
	s_waitcnt lgkmcnt(4)
	v_mfma_f32_32x32x16_bf16 v[32:47], v[180:183], v[184:187], v[32:47]
	s_waitcnt lgkmcnt(2)
	v_mfma_f32_32x32x16_bf16 v[32:47], v[188:191], v[192:195], v[32:47]
	s_waitcnt lgkmcnt(0)
	v_mfma_f32_32x32x16_bf16 v[32:47], v[196:199], v[200:203], v[32:47]
	s_nop 11
	ds_write2_b32 v153, v32, v33 offset1:132
	v_add_u32_e32 v32, 0x400, v153
	ds_write2_b32 v32, v34, v35 offset0:8 offset1:140
	v_add_u32_e32 v32, 0x1000, v153
	ds_write2_b32 v32, v36, v37 offset0:32 offset1:164
	v_add_u32_e32 v32, 0x1400, v153
	ds_write2_b32 v32, v38, v39 offset0:40 offset1:172
	v_add_u32_e32 v32, 0x2000, v153
	ds_write2_b32 v32, v40, v41 offset0:64 offset1:196
	v_add_u32_e32 v32, 0x2400, v153
	ds_write2_b32 v32, v42, v43 offset0:72 offset1:204
	v_add_u32_e32 v32, 0x3000, v153
	ds_write2_b32 v32, v44, v45 offset0:96 offset1:228
	v_add_u32_e32 v32, 0x3400, v153
	ds_write2_b32 v32, v46, v47 offset0:104 offset1:236
	v_add_u32_e32 v220, s96, v128
	ds_read_b128 v[32:35], v220
	ds_read_b128 v[36:39], v220 offset:32
	ds_read_b128 v[40:43], v220 offset:64
	ds_read_b128 v[44:47], v220 offset:96
	ds_read_b128 v[172:175], v154 offset:52224
	ds_read_b128 v[188:191], v155
	ds_read_b128 v[204:207], v155 offset:4608
	ds_read_b128 v[176:179], v154 offset:52256
	ds_read_b128 v[192:195], v155 offset:32
	ds_read_b128 v[208:211], v155 offset:4640
	s_waitcnt lgkmcnt(9)
	v_pk_mul_f32 v[0:1], v[0:1], v[32:33]
	v_pk_mul_f32 v[2:3], v[2:3], v[34:35]
	v_pk_mul_f32 v[16:17], v[16:17], v[32:33]
	v_pk_mul_f32 v[18:19], v[18:19], v[34:35]
	s_waitcnt lgkmcnt(8)
	v_pk_mul_f32 v[4:5], v[4:5], v[36:37]
	v_pk_mul_f32 v[6:7], v[6:7], v[38:39]
	v_pk_mul_f32 v[20:21], v[20:21], v[36:37]
	v_pk_mul_f32 v[22:23], v[22:23], v[38:39]
	s_waitcnt lgkmcnt(7)
	v_pk_mul_f32 v[8:9], v[8:9], v[40:41]
	v_pk_mul_f32 v[10:11], v[10:11], v[42:43]
	v_pk_mul_f32 v[24:25], v[24:25], v[40:41]
	v_pk_mul_f32 v[26:27], v[26:27], v[42:43]
	s_waitcnt lgkmcnt(6)
	v_pk_mul_f32 v[12:13], v[12:13], v[44:45]
	v_pk_mul_f32 v[14:15], v[14:15], v[46:47]
	v_pk_mul_f32 v[28:29], v[28:29], v[44:45]
	v_pk_mul_f32 v[30:31], v[30:31], v[46:47]
	ds_read_b128 v[180:183], v154 offset:52288
	ds_read_b128 v[196:199], v155 offset:64
	ds_read_b128 v[212:215], v155 offset:4672
	ds_read_b128 v[184:187], v154 offset:52320
	ds_read_b128 v[200:203], v155 offset:96
	ds_read_b128 v[216:219], v155 offset:4704
	s_waitcnt lgkmcnt(10)
	v_mfma_f32_32x32x16_bf16 v[0:15], v[172:175], v[188:191], v[0:15]
	s_waitcnt lgkmcnt(9)
	v_mfma_f32_32x32x16_bf16 v[16:31], v[172:175], v[204:207], v[16:31]
	s_waitcnt lgkmcnt(7)
	v_mfma_f32_32x32x16_bf16 v[0:15], v[176:179], v[192:195], v[0:15]
	s_waitcnt lgkmcnt(6)
	v_mfma_f32_32x32x16_bf16 v[16:31], v[176:179], v[208:211], v[16:31]
	s_waitcnt lgkmcnt(4)
	v_mfma_f32_32x32x16_bf16 v[0:15], v[180:183], v[196:199], v[0:15]
	s_waitcnt lgkmcnt(3)
	v_mfma_f32_32x32x16_bf16 v[16:31], v[180:183], v[212:215], v[16:31]
	s_waitcnt lgkmcnt(1)
	v_mfma_f32_32x32x16_bf16 v[0:15], v[184:187], v[200:203], v[0:15]
	s_waitcnt lgkmcnt(0)
	s_barrier
; #define LAS __attribute__((address_space(3)))
; __device__ __forceinline__ unsigned pk2(float lo, float hi) { typedef float f2v __attribute__((ext_vector_type(2))); typedef __bf16 b2v __attribute__((ext_vector_type(2))); const f2v v = {lo, hi}; const b2v b = __builtin_convertvector(v, b2v); return __builtin_bit_cast(unsigned, b); }
; __device__ __forceinline__ u32x4 pack8(const float (&f)[8]) { u32x4 w; w.x = pk2(f[0], f[1]); w.y = pk2(f[2], f[3]); w.z = pk2(f[4], f[5]); w.w = pk2(f[6], f[7]); return w; }
; template <bool FULL, bool STORE = true>
; __device__ __forceinline__ void hg_item(const Prm& P, LAS unsigned char* lds, int item, int wave) {
;     ...
;             for (int i = 0; i < 2; ++i) { const bf16x8 bb = *(const LAS bf16x8*)(lds + HL_IVT + ((vb0 + i) * 32 + l31) * 144 + ks * 32 + lh * 16); S[i] = __builtin_amdgcn_mfma_f32_32x32x16_bf16(a, bb, S[i], 0, 0, 0); } }
;         if (FULL) {
;             __syncthreads();
; #pragma unroll
;             for (int i = 0; i < 2; ++i)
; #pragma unroll
;                 for (int g4 = 0; g4 < 4; ++g4) { u32x2 w; w.x = pk2(S[i][4 * g4], S[i][4 * g4 + 1]); w.y = pk2(S[i][4 * g4 + 2], S[i][4 * g4 + 3]);
;                     *(LAS u32x2*)(lds + HL_ST + ((vb0 + i) * 32 + l31) * 272 + (kb * 32 + 8 * g4 + 4 * lh) * 2) = w; }
;             { const int t = tid >> 3, vs = (tid & 7) * 16; float o[16]; float ss = 0.f;
; #pragma unroll
;                 for (int q4 = 0; q4 < 4; ++q4) { const f32x4 x4 = *(const LAS f32x4*)(lds + HL_OS + t * 528 + (vs + 4 * q4) * 4);
; #pragma unroll
;                     for (int j = 0; j < 4; ++j) { o[4 * q4 + j] = x4[j]; ss += x4[j] * x4[j]; } }
;                 ss += __shfl_xor(ss, 1); ss += __shfl_xor(ss, 2); ss += __shfl_xor(ss, 4);
;                 const float r = rsqrtf(ss * (1.0f / 128.0f) + EPS);
;                 const size_t oo = (row0 + t) * 1024 + h * 128 + vs; const float* gn = P.in[I_HGNG] + h * 128 + vs;
;                 float g0[8], g1[8]; unpack8(gcur0, g0); unpack8(gcur1, g1);
;                 float w0[8], w1[8];
; #pragma unroll
;                 for (int j = 0; j < 8; ++j) { w0[j] = o[j] * r * gn[j] * g0[j]; w1[j] = o[8 + j] * r * gn[8 + j] * g1[j]; }
;                 if (STORE) { *(u32x4*)(AHG + oo) = pack8(w0); *(u32x4*)(AHG + oo + 8) = pack8(w1); }
	v_mfma_f32_32x32x16_bf16 v[16:31], v[184:187], v[216:219], v[16:31]
	s_nop 8
	v_cvt_pk_bf16_f32 v32, v0, v1
	v_cvt_pk_bf16_f32 v33, v2, v3
	v_cvt_pk_bf16_f32 v34, v4, v5
	v_cvt_pk_bf16_f32 v35, v6, v7
	ds_write2_b64 v156, v[32:33], v[34:35] offset1:2
	v_cvt_pk_bf16_f32 v32, v8, v9
	v_cvt_pk_bf16_f32 v33, v10, v11
	v_cvt_pk_bf16_f32 v34, v12, v13
	v_cvt_pk_bf16_f32 v35, v14, v15
	ds_write2_b64 v156, v[32:33], v[34:35] offset0:4 offset1:6
	v_cvt_pk_bf16_f32 v32, v16, v17
	v_cvt_pk_bf16_f32 v33, v18, v19
	v_cvt_pk_bf16_f32 v34, v20, v21
	v_cvt_pk_bf16_f32 v35, v22, v23
	v_add_u32_e32 v36, 0x2000, v156
	ds_write2_b64 v36, v[32:33], v[34:35] offset0:64 offset1:66
	v_cvt_pk_bf16_f32 v32, v24, v25
	v_cvt_pk_bf16_f32 v33, v26, v27
	v_cvt_pk_bf16_f32 v34, v28, v29
	v_cvt_pk_bf16_f32 v35, v30, v31
	ds_write2_b64 v36, v[32:33], v[34:35] offset0:68 offset1:70
	ds_read_b128 v[66:69], v157
	ds_read_b128 v[36:39], v157 offset:16
	ds_read_b128 v[44:47], v157 offset:32
	ds_read_b128 v[32:35], v157 offset:48
	s_waitcnt lgkmcnt(3)
	v_mul_f32_e32 v64, v67, v67
	v_fmac_f32_e32 v64, v66, v66
	v_fmac_f32_e32 v64, v68, v68
	v_fmac_f32_e32 v64, v69, v69
	s_waitcnt lgkmcnt(2)
	v_fmac_f32_e32 v64, v36, v36
	v_fmac_f32_e32 v64, v37, v37
	v_fmac_f32_e32 v64, v38, v38
	v_fmac_f32_e32 v64, v39, v39
	s_waitcnt lgkmcnt(1)
	v_pk_mul_f32 v[42:43], v[44:45], v[44:45]
	v_pk_mul_f32 v[40:41], v[46:47], v[46:47]
	v_add_f32_e32 v42, v42, v64
	v_add_f32_e32 v42, v43, v42
	v_add_f32_e32 v40, v40, v42
	v_add_f32_e32 v64, v41, v40
	s_waitcnt lgkmcnt(0)
	v_pk_mul_f32 v[42:43], v[32:33], v[32:33]
	v_pk_mul_f32 v[40:41], v[34:35], v[34:35]
	v_add_f32_e32 v42, v42, v64
	v_add_f32_e32 v42, v43, v42
	v_add_f32_e32 v40, v40, v42
	v_add_f32_e32 v40, v41, v40
	ds_bpermute_b32 v41, v129, v40
	s_waitcnt lgkmcnt(0)
	v_add_f32_e32 v40, v40, v41
	ds_bpermute_b32 v41, v130, v40
	s_waitcnt lgkmcnt(0)
	v_add_f32_e32 v40, v40, v41
	ds_bpermute_b32 v41, v131, v40
	s_waitcnt lgkmcnt(0)
	v_add_f32_e32 v40, v40, v41
	v_fmamk_f32 v40, v40, 0x3c000000, v109
	v_cmp_gt_f32_e32 vcc, s33, v40
	v_mul_f32_e32 v41, 0x4b800000, v40
	s_mov_b32 s33, 0x7400000
	v_cndmask_b32_e32 v40, v40, v41, vcc
	v_rsq_f32_e32 v40, v40
	s_nop 0
	v_mul_f32_e32 v41, 0x45800000, v40
	v_cndmask_b32_e32 v74, v40, v41, vcc
	v_pk_mul_f32 v[106:107], v[66:67], v[74:75] op_sel_hi:[1,0]
	v_pk_mul_f32 v[46:47], v[46:47], v[74:75] op_sel_hi:[1,0]
	v_pk_mul_f32 v[36:37], v[36:37], v[74:75] op_sel_hi:[1,0]
	v_pk_mul_f32 v[32:33], v[32:33], v[74:75] op_sel_hi:[1,0]
	v_pk_mul_f32 v[44:45], v[44:45], v[74:75] op_sel_hi:[1,0]
	v_pk_mul_f32 v[38:39], v[38:39], v[74:75] op_sel_hi:[1,0]
	v_pk_mul_f32 v[34:35], v[34:35], v[74:75] op_sel_hi:[1,0]
	s_waitcnt vmcnt(0)
	v_pk_mul_f32 v[32:33], v[224:225], v[32:33]
	v_pk_mul_f32 v[46:47], v[230:231], v[46:47]
	v_pk_mul_f32 v[36:37], v[232:233], v[36:37]
	v_pk_mul_f32 v[106:107], v[236:237], v[106:107]
	v_pk_mul_f32 v[44:45], v[228:229], v[44:45]
	v_pk_mul_f32 v[104:105], v[106:107], v[104:105]
	v_lshlrev_b32_e32 v106, 16, v48
	v_and_b32_e32 v107, 0xffff0000, v48
	v_lshlrev_b32_e32 v48, 16, v49
	v_and_b32_e32 v49, 0xffff0000, v49
	v_pk_mul_f32 v[46:47], v[46:47], v[48:49]
	v_lshlrev_b32_e32 v48, 16, v54
	v_and_b32_e32 v49, 0xffff0000, v54
	v_pk_mul_f32 v[36:37], v[36:37], v[48:49]
	v_lshlrev_b32_e32 v48, 16, v50
	v_and_b32_e32 v49, 0xffff0000, v50
	v_pk_mul_f32 v[64:65], v[68:69], v[74:75] op_sel_hi:[1,0]
	v_pk_mul_f32 v[40:41], v[32:33], v[48:49]
	v_lshlrev_b32_e32 v32, 16, v55
	v_and_b32_e32 v33, 0xffff0000, v55
	v_pk_mul_f32 v[38:39], v[234:235], v[38:39]
	v_pk_mul_f32 v[64:65], v[238:239], v[64:65]
	v_pk_mul_f32 v[38:39], v[38:39], v[32:33]
	v_lshlrev_b32_e32 v32, 16, v51
	v_and_b32_e32 v33, 0xffff0000, v51
	v_pk_mul_f32 v[34:35], v[226:227], v[34:35]
	v_pk_mul_f32 v[52:53], v[64:65], v[52:53]
	v_pk_mul_f32 v[42:43], v[34:35], v[32:33]
	v_cvt_pk_bf16_f32 v34, v36, v37
	v_add_co_u32_e32 v36, vcc, s33, v102
	v_pk_mul_f32 v[44:45], v[44:45], v[106:107]
	v_cvt_pk_bf16_f32 v32, v104, v105
	v_cvt_pk_bf16_f32 v33, v52, v53
	v_cvt_pk_bf16_f32 v35, v38, v39
	v_addc_co_u32_e32 v37, vcc, 0, v103, vcc
	v_mov_b64_e32 v[52:53], v[56:57]
	v_mov_b64_e32 v[48:49], v[60:61]
	global_store_dwordx4 v[36:37], v[32:35], off
	v_mov_b64_e32 v[54:55], v[58:59]
	v_mov_b64_e32 v[50:51], v[62:63]
	v_cvt_pk_bf16_f32 v32, v44, v45
	v_cvt_pk_bf16_f32 v33, v46, v47
	v_cvt_pk_bf16_f32 v34, v40, v41
	v_cvt_pk_bf16_f32 v35, v42, v43
	global_store_dwordx4 v[36:37], v[32:35], off offset:16
	v_cvt_f32_f16_e32 v78, v240
	v_cvt_f32_f16_sdwa v79, v240 dst_sel:DWORD dst_unused:UNUSED_PAD src0_sel:WORD_1
	v_cvt_f32_f16_e32 v80, v241
	v_cvt_f32_f16_sdwa v81, v241 dst_sel:DWORD dst_unused:UNUSED_PAD src0_sel:WORD_1
	v_cvt_f32_f16_e32 v82, v242
	v_cvt_f32_f16_sdwa v83, v242 dst_sel:DWORD dst_unused:UNUSED_PAD src0_sel:WORD_1
	v_cvt_f32_f16_e32 v84, v243
	v_cvt_f32_f16_sdwa v85, v243 dst_sel:DWORD dst_unused:UNUSED_PAD src0_sel:WORD_1
	v_cvt_f32_f16_e32 v86, v244
	v_cvt_f32_f16_sdwa v87, v244 dst_sel:DWORD dst_unused:UNUSED_PAD src0_sel:WORD_1
	v_cvt_f32_f16_e32 v88, v245
	v_cvt_f32_f16_sdwa v89, v245 dst_sel:DWORD dst_unused:UNUSED_PAD src0_sel:WORD_1
	v_cvt_f32_f16_e32 v90, v246
	v_cvt_f32_f16_sdwa v91, v246 dst_sel:DWORD dst_unused:UNUSED_PAD src0_sel:WORD_1
	v_cvt_f32_f16_e32 v92, v247
	v_cvt_f32_f16_sdwa v93, v247 dst_sel:DWORD dst_unused:UNUSED_PAD src0_sel:WORD_1
	s_cbranch_scc0 .LBB0_821
